# XG written by the FFN1-down epilogue in GEMM-image layout (16 KiB per 128x64 block); w_in GEMM stages its A operand with full-line 1 KiB pieces
# baseline (speedup 1.0000x reference)
.LBB0_468:
	v_lshl_add_u32 v158, s49, 8, v162
	v_lshl_or_b32 v159, s47, 8, v164
	v_lshlrev_b32_e32 v160, 2, v159
	v_lshl_add_u32 v156, v158, 12, v160
	global_load_dwordx4 v[54:57], v160, s[16:17]
	global_load_dwordx4 v[50:53], v160, s[16:17] offset:16
	global_load_dwordx4 v[30:33], v160, s[16:17] offset:512
	global_load_dwordx4 v[26:29], v160, s[16:17] offset:528
	global_load_dwordx4 v[188:191], v156, s[0:1]
	global_load_dwordx4 v[192:195], v156, s[0:1] offset:16
	global_load_dwordx4 v[196:199], v156, s[0:1] offset:512
	global_load_dwordx4 v[200:203], v156, s[0:1] offset:528
	v_add_u32_e32 v157, 0x10000, v156
	global_load_dwordx4 v[204:207], v157, s[0:1]
	global_load_dwordx4 v[208:211], v157, s[0:1] offset:16
	global_load_dwordx4 v[212:215], v157, s[0:1] offset:512
	global_load_dwordx4 v[216:219], v157, s[0:1] offset:528
	s_lshl_b32 s24, s47, 2
	s_add_i32 s24, s24, s41
	s_lshl_b32 s24, s24, 2
	v_lshlrev_b32_e32 v174, 6, v158
	v_add_u32_e32 v174, s24, v174
	v_mbcnt_hi_u32_b32 v166, -1, v253
	v_xor_b32_e32 v167, 32, v166
	v_xor_b32_e32 v166, 16, v166
	v_lshlrev_b32_e32 v166, 2, v166
	v_lshlrev_b32_e32 v167, 2, v167
	v_and_b32_e32 v175, 15, v162
	v_lshlrev_b32_e32 v184, 6, v175
	v_bfe_u32 v185, v164, 3, 2
	v_lshl_add_u32 v184, v185, 4, v184
	v_and_b32_e32 v185, 8, v175
	v_lshlrev_b32_e32 v185, 2, v185
	v_xor_b32_e32 v184, v184, v185
	v_lshrrev_b32_e32 v185, 5, v164
	v_and_b32_e32 v186, 1, v185
	v_lshl_add_u32 v184, v186, 10, v184
	v_lshrrev_b32_e32 v185, 1, v185
	v_lshl_add_u32 v184, v185, 14, v184
	v_lshrrev_b32_e32 v185, 6, v162
	v_lshl_add_u32 v184, v185, 13, v184
	s_lshl_b32 s92, s49, 5
	s_lshl_b32 s25, s47, 2
	s_add_i32 s92, s92, s25
	s_lshl_b32 s92, s92, 14
	v_add_u32_e32 v184, s92, v184
	s_waitcnt vmcnt(4)
	v_pk_fma_f32 v[142:143], v[142:143], 0.5, v[188:189] op_sel_hi:[1,0,1]
	v_pk_fma_f32 v[144:145], v[144:145], 0.5, v[190:191] op_sel_hi:[1,0,1]
	v_pk_fma_f32 v[138:139], v[138:139], 0.5, v[192:193] op_sel_hi:[1,0,1]
	v_pk_fma_f32 v[140:141], v[140:141], 0.5, v[194:195] op_sel_hi:[1,0,1]
	v_pk_fma_f32 v[134:135], v[134:135], 0.5, v[196:197] op_sel_hi:[1,0,1]
	v_pk_fma_f32 v[136:137], v[136:137], 0.5, v[198:199] op_sel_hi:[1,0,1]
	v_pk_fma_f32 v[130:131], v[130:131], 0.5, v[200:201] op_sel_hi:[1,0,1]
	v_pk_fma_f32 v[132:133], v[132:133], 0.5, v[202:203] op_sel_hi:[1,0,1]
	v_add_u32_e32 v157, 0x20000, v156
	global_load_dwordx4 v[188:191], v157, s[0:1]
	global_load_dwordx4 v[192:195], v157, s[0:1] offset:16
	global_load_dwordx4 v[196:199], v157, s[0:1] offset:512
	global_load_dwordx4 v[200:203], v157, s[0:1] offset:528
	v_mov_b32_e32 v159, v156
	global_store_dwordx4 v159, v[142:145], s[12:13]
	global_store_dwordx4 v159, v[138:141], s[12:13] offset:16
	global_store_dwordx4 v159, v[134:137], s[12:13] offset:512
	global_store_dwordx4 v159, v[130:133], s[12:13] offset:528
	v_mul_f32_e32 v169, v145, v145
	v_mul_f32_e32 v168, v143, v143
	v_fmac_f32_e32 v168, v142, v142
	v_fmac_f32_e32 v169, v144, v144
	v_add_f32_e32 v168, v168, v169
	v_mul_f32_e32 v169, v139, v139
	v_fmac_f32_e32 v169, v138, v138
	v_add_f32_e32 v168, v169, v168
	v_mul_f32_e32 v169, v141, v141
	v_fmac_f32_e32 v169, v140, v140
	v_add_f32_e32 v170, v169, v168
	v_mul_f32_e32 v169, v137, v137
	v_mul_f32_e32 v168, v135, v135
	v_fmac_f32_e32 v168, v134, v134
	v_fmac_f32_e32 v169, v136, v136
	v_add_f32_e32 v168, v168, v169
	v_mul_f32_e32 v169, v131, v131
	v_fmac_f32_e32 v169, v130, v130
	v_add_f32_e32 v168, v169, v168
	v_mul_f32_e32 v169, v133, v133
	v_fmac_f32_e32 v169, v132, v132
	v_add_f32_e32 v168, v169, v168
	v_add_f32_e32 v168, v170, v168
	ds_bpermute_b32 v169, v166, v168
	v_pk_mul_f32 v[142:143], v[54:55], v[142:143]
	v_pk_mul_f32 v[144:145], v[56:57], v[144:145]
	v_pk_mul_f32 v[138:139], v[50:51], v[138:139]
	v_pk_mul_f32 v[140:141], v[52:53], v[140:141]
	v_cvt_pk_bf16_f32 v142, v142, v143
	v_cvt_pk_bf16_f32 v143, v144, v145
	v_cvt_pk_bf16_f32 v144, v138, v139
	v_cvt_pk_bf16_f32 v145, v140, v141
	v_pk_mul_f32 v[134:135], v[30:31], v[134:135]
	v_pk_mul_f32 v[136:137], v[32:33], v[136:137]
	v_pk_mul_f32 v[130:131], v[26:27], v[130:131]
	v_pk_mul_f32 v[132:133], v[28:29], v[132:133]
	v_cvt_pk_bf16_f32 v134, v134, v135
	v_cvt_pk_bf16_f32 v135, v136, v137
	v_cvt_pk_bf16_f32 v136, v130, v131
	v_cvt_pk_bf16_f32 v137, v132, v133
	v_mov_b32_e32 v160, v184
	v_add_u32_e32 v185, 0x8000, v160
	global_store_dwordx4 v160, v[142:145], s[18:19]
	global_store_dwordx4 v185, v[134:137], s[18:19]
	s_waitcnt lgkmcnt(0)
	v_add_f32_e32 v169, v168, v169
	ds_bpermute_b32 v170, v167, v169
	v_mov_b32_e32 v161, v174
	s_waitcnt lgkmcnt(0)
	v_add_f32_e32 v169, v169, v170
	s_and_saveexec_b64 s[2:3], s[6:7]
	global_store_dword v161, v169, s[14:15]
	s_or_b64 exec, exec, s[2:3]
	v_add_u32_e32 v157, 0x30000, v156
	global_load_dwordx4 v[142:145], v157, s[0:1]
	global_load_dwordx4 v[138:141], v157, s[0:1] offset:16
	global_load_dwordx4 v[134:137], v157, s[0:1] offset:512
	global_load_dwordx4 v[130:133], v157, s[0:1] offset:528
	s_waitcnt vmcnt(15)
	v_pk_fma_f32 v[126:127], v[126:127], 0.5, v[204:205] op_sel_hi:[1,0,1]
	v_pk_fma_f32 v[128:129], v[128:129], 0.5, v[206:207] op_sel_hi:[1,0,1]
	v_pk_fma_f32 v[122:123], v[122:123], 0.5, v[208:209] op_sel_hi:[1,0,1]
	v_pk_fma_f32 v[124:125], v[124:125], 0.5, v[210:211] op_sel_hi:[1,0,1]
	v_pk_fma_f32 v[118:119], v[118:119], 0.5, v[212:213] op_sel_hi:[1,0,1]
	v_pk_fma_f32 v[120:121], v[120:121], 0.5, v[214:215] op_sel_hi:[1,0,1]
	v_pk_fma_f32 v[114:115], v[114:115], 0.5, v[216:217] op_sel_hi:[1,0,1]
	v_pk_fma_f32 v[116:117], v[116:117], 0.5, v[218:219] op_sel_hi:[1,0,1]
	v_add_u32_e32 v157, 0x80000, v156
	global_load_dwordx4 v[204:207], v157, s[0:1]
	global_load_dwordx4 v[208:211], v157, s[0:1] offset:16
	global_load_dwordx4 v[212:215], v157, s[0:1] offset:512
	global_load_dwordx4 v[216:219], v157, s[0:1] offset:528
	v_add_u32_e32 v159, 0x10000, v156
	global_store_dwordx4 v159, v[126:129], s[12:13]
	global_store_dwordx4 v159, v[122:125], s[12:13] offset:16
	global_store_dwordx4 v159, v[118:121], s[12:13] offset:512
	global_store_dwordx4 v159, v[114:117], s[12:13] offset:528
	v_mul_f32_e32 v169, v129, v129
	v_mul_f32_e32 v168, v127, v127
	v_fmac_f32_e32 v168, v126, v126
	v_fmac_f32_e32 v169, v128, v128
	v_add_f32_e32 v168, v168, v169
	v_mul_f32_e32 v169, v123, v123
	v_fmac_f32_e32 v169, v122, v122
	v_add_f32_e32 v168, v169, v168
	v_mul_f32_e32 v169, v125, v125
	v_fmac_f32_e32 v169, v124, v124
	v_add_f32_e32 v170, v169, v168
	v_mul_f32_e32 v169, v121, v121
	v_mul_f32_e32 v168, v119, v119
	v_fmac_f32_e32 v168, v118, v118
	v_fmac_f32_e32 v169, v120, v120
	v_add_f32_e32 v168, v168, v169
	v_mul_f32_e32 v169, v115, v115
	v_fmac_f32_e32 v169, v114, v114
	v_add_f32_e32 v168, v169, v168
	v_mul_f32_e32 v169, v117, v117
	v_fmac_f32_e32 v169, v116, v116
	v_add_f32_e32 v168, v169, v168
	v_add_f32_e32 v168, v170, v168
	ds_bpermute_b32 v169, v166, v168
	v_pk_mul_f32 v[126:127], v[54:55], v[126:127]
	v_pk_mul_f32 v[128:129], v[56:57], v[128:129]
	v_pk_mul_f32 v[122:123], v[50:51], v[122:123]
	v_pk_mul_f32 v[124:125], v[52:53], v[124:125]
	v_cvt_pk_bf16_f32 v126, v126, v127
	v_cvt_pk_bf16_f32 v127, v128, v129
	v_cvt_pk_bf16_f32 v128, v122, v123
	v_cvt_pk_bf16_f32 v129, v124, v125
	v_pk_mul_f32 v[118:119], v[30:31], v[118:119]
	v_pk_mul_f32 v[120:121], v[32:33], v[120:121]
	v_pk_mul_f32 v[114:115], v[26:27], v[114:115]
	v_pk_mul_f32 v[116:117], v[28:29], v[116:117]
	v_cvt_pk_bf16_f32 v118, v118, v119
	v_cvt_pk_bf16_f32 v119, v120, v121
	v_cvt_pk_bf16_f32 v120, v114, v115
	v_cvt_pk_bf16_f32 v121, v116, v117
	v_add_u32_e32 v160, 0x800, v184
	v_add_u32_e32 v185, 0x8000, v160
	global_store_dwordx4 v160, v[126:129], s[18:19]
	global_store_dwordx4 v185, v[118:121], s[18:19]
	s_waitcnt lgkmcnt(0)
	v_add_f32_e32 v169, v168, v169
	ds_bpermute_b32 v170, v167, v169
	v_add_u32_e32 v161, 0x400, v174
	s_waitcnt lgkmcnt(0)
	v_add_f32_e32 v169, v169, v170
	s_and_saveexec_b64 s[2:3], s[6:7]
	global_store_dword v161, v169, s[14:15]
	s_or_b64 exec, exec, s[2:3]
	v_add_u32_e32 v157, 0x90000, v156
	global_load_dwordx4 v[126:129], v157, s[0:1]
	global_load_dwordx4 v[122:125], v157, s[0:1] offset:16
	global_load_dwordx4 v[118:121], v157, s[0:1] offset:512
	global_load_dwordx4 v[114:117], v157, s[0:1] offset:528
	s_waitcnt vmcnt(26)
	v_pk_fma_f32 v[110:111], v[110:111], 0.5, v[188:189] op_sel_hi:[1,0,1]
	v_pk_fma_f32 v[112:113], v[112:113], 0.5, v[190:191] op_sel_hi:[1,0,1]
	v_pk_fma_f32 v[106:107], v[106:107], 0.5, v[192:193] op_sel_hi:[1,0,1]
	v_pk_fma_f32 v[108:109], v[108:109], 0.5, v[194:195] op_sel_hi:[1,0,1]
	v_pk_fma_f32 v[102:103], v[102:103], 0.5, v[196:197] op_sel_hi:[1,0,1]
	v_pk_fma_f32 v[104:105], v[104:105], 0.5, v[198:199] op_sel_hi:[1,0,1]
	v_pk_fma_f32 v[98:99], v[98:99], 0.5, v[200:201] op_sel_hi:[1,0,1]
	v_pk_fma_f32 v[100:101], v[100:101], 0.5, v[202:203] op_sel_hi:[1,0,1]
	v_add_u32_e32 v157, 0xa0000, v156
	global_load_dwordx4 v[188:191], v157, s[0:1]
	global_load_dwordx4 v[192:195], v157, s[0:1] offset:16
	global_load_dwordx4 v[196:199], v157, s[0:1] offset:512
	global_load_dwordx4 v[200:203], v157, s[0:1] offset:528
	v_add_u32_e32 v159, 0x20000, v156
	global_store_dwordx4 v159, v[110:113], s[12:13]
	global_store_dwordx4 v159, v[106:109], s[12:13] offset:16
	global_store_dwordx4 v159, v[102:105], s[12:13] offset:512
	global_store_dwordx4 v159, v[98:101], s[12:13] offset:528
	v_mul_f32_e32 v169, v113, v113
	v_mul_f32_e32 v168, v111, v111
	v_fmac_f32_e32 v168, v110, v110
	v_fmac_f32_e32 v169, v112, v112
	v_add_f32_e32 v168, v168, v169
	v_mul_f32_e32 v169, v107, v107
	v_fmac_f32_e32 v169, v106, v106
	v_add_f32_e32 v168, v169, v168
	v_mul_f32_e32 v169, v109, v109
	v_fmac_f32_e32 v169, v108, v108
	v_add_f32_e32 v170, v169, v168
	v_mul_f32_e32 v169, v105, v105
	v_mul_f32_e32 v168, v103, v103
	v_fmac_f32_e32 v168, v102, v102
	v_fmac_f32_e32 v169, v104, v104
	v_add_f32_e32 v168, v168, v169
	v_mul_f32_e32 v169, v99, v99
	v_fmac_f32_e32 v169, v98, v98
	v_add_f32_e32 v168, v169, v168
	v_mul_f32_e32 v169, v101, v101
	v_fmac_f32_e32 v169, v100, v100
	v_add_f32_e32 v168, v169, v168
	v_add_f32_e32 v168, v170, v168
	ds_bpermute_b32 v169, v166, v168
	v_pk_mul_f32 v[110:111], v[54:55], v[110:111]
	v_pk_mul_f32 v[112:113], v[56:57], v[112:113]
	v_pk_mul_f32 v[106:107], v[50:51], v[106:107]
	v_pk_mul_f32 v[108:109], v[52:53], v[108:109]
	v_cvt_pk_bf16_f32 v110, v110, v111
	v_cvt_pk_bf16_f32 v111, v112, v113
	v_cvt_pk_bf16_f32 v112, v106, v107
	v_cvt_pk_bf16_f32 v113, v108, v109
	v_pk_mul_f32 v[102:103], v[30:31], v[102:103]
	v_pk_mul_f32 v[104:105], v[32:33], v[104:105]
	v_pk_mul_f32 v[98:99], v[26:27], v[98:99]
	v_pk_mul_f32 v[100:101], v[28:29], v[100:101]
	v_cvt_pk_bf16_f32 v102, v102, v103
	v_cvt_pk_bf16_f32 v103, v104, v105
	v_cvt_pk_bf16_f32 v104, v98, v99
	v_cvt_pk_bf16_f32 v105, v100, v101
	v_add_u32_e32 v160, 0x1000, v184
	v_add_u32_e32 v185, 0x8000, v160
	global_store_dwordx4 v160, v[110:113], s[18:19]
	global_store_dwordx4 v185, v[102:105], s[18:19]
	s_waitcnt lgkmcnt(0)
	v_add_f32_e32 v169, v168, v169
	ds_bpermute_b32 v170, v167, v169
	v_add_u32_e32 v161, 0x800, v174
	s_waitcnt lgkmcnt(0)
	v_add_f32_e32 v169, v169, v170
	s_and_saveexec_b64 s[2:3], s[6:7]
	global_store_dword v161, v169, s[14:15]
	s_or_b64 exec, exec, s[2:3]
	v_add_u32_e32 v157, 0xb0000, v156
	global_load_dwordx4 v[110:113], v157, s[0:1]
	global_load_dwordx4 v[106:109], v157, s[0:1] offset:16
	global_load_dwordx4 v[102:105], v157, s[0:1] offset:512
	global_load_dwordx4 v[98:101], v157, s[0:1] offset:528
	s_waitcnt vmcnt(30)
	v_pk_fma_f32 v[94:95], v[94:95], 0.5, v[142:143] op_sel_hi:[1,0,1]
	v_pk_fma_f32 v[96:97], v[96:97], 0.5, v[144:145] op_sel_hi:[1,0,1]
	v_pk_fma_f32 v[90:91], v[90:91], 0.5, v[138:139] op_sel_hi:[1,0,1]
	v_pk_fma_f32 v[92:93], v[92:93], 0.5, v[140:141] op_sel_hi:[1,0,1]
	v_pk_fma_f32 v[86:87], v[86:87], 0.5, v[134:135] op_sel_hi:[1,0,1]
	v_pk_fma_f32 v[88:89], v[88:89], 0.5, v[136:137] op_sel_hi:[1,0,1]
	v_pk_fma_f32 v[82:83], v[82:83], 0.5, v[130:131] op_sel_hi:[1,0,1]
	v_pk_fma_f32 v[84:85], v[84:85], 0.5, v[132:133] op_sel_hi:[1,0,1]
	v_add_u32_e32 v159, 0x30000, v156
	global_store_dwordx4 v159, v[94:97], s[12:13]
	global_store_dwordx4 v159, v[90:93], s[12:13] offset:16
	global_store_dwordx4 v159, v[86:89], s[12:13] offset:512
	global_store_dwordx4 v159, v[82:85], s[12:13] offset:528
	v_mul_f32_e32 v169, v97, v97
	v_mul_f32_e32 v168, v95, v95
	v_fmac_f32_e32 v168, v94, v94
	v_fmac_f32_e32 v169, v96, v96
	v_add_f32_e32 v168, v168, v169
	v_mul_f32_e32 v169, v91, v91
	v_fmac_f32_e32 v169, v90, v90
	v_add_f32_e32 v168, v169, v168
	v_mul_f32_e32 v169, v93, v93
	v_fmac_f32_e32 v169, v92, v92
	v_add_f32_e32 v170, v169, v168
	v_mul_f32_e32 v169, v89, v89
	v_mul_f32_e32 v168, v87, v87
	v_fmac_f32_e32 v168, v86, v86
	v_fmac_f32_e32 v169, v88, v88
	v_add_f32_e32 v168, v168, v169
	v_mul_f32_e32 v169, v83, v83
	v_fmac_f32_e32 v169, v82, v82
	v_add_f32_e32 v168, v169, v168
	v_mul_f32_e32 v169, v85, v85
	v_fmac_f32_e32 v169, v84, v84
	v_add_f32_e32 v168, v169, v168
	v_add_f32_e32 v168, v170, v168
	ds_bpermute_b32 v169, v166, v168
	v_pk_mul_f32 v[94:95], v[54:55], v[94:95]
	v_pk_mul_f32 v[96:97], v[56:57], v[96:97]
	v_pk_mul_f32 v[90:91], v[50:51], v[90:91]
	v_pk_mul_f32 v[92:93], v[52:53], v[92:93]
	v_cvt_pk_bf16_f32 v94, v94, v95
	v_cvt_pk_bf16_f32 v95, v96, v97
	v_cvt_pk_bf16_f32 v96, v90, v91
	v_cvt_pk_bf16_f32 v97, v92, v93
	v_pk_mul_f32 v[86:87], v[30:31], v[86:87]
	v_pk_mul_f32 v[88:89], v[32:33], v[88:89]
	v_pk_mul_f32 v[82:83], v[26:27], v[82:83]
	v_pk_mul_f32 v[84:85], v[28:29], v[84:85]
	v_cvt_pk_bf16_f32 v86, v86, v87
	v_cvt_pk_bf16_f32 v87, v88, v89
	v_cvt_pk_bf16_f32 v88, v82, v83
	v_cvt_pk_bf16_f32 v89, v84, v85
	v_add_u32_e32 v160, 0x1800, v184
	v_add_u32_e32 v185, 0x8000, v160
	global_store_dwordx4 v160, v[94:97], s[18:19]
	global_store_dwordx4 v185, v[86:89], s[18:19]
	s_waitcnt lgkmcnt(0)
	v_add_f32_e32 v169, v168, v169
	ds_bpermute_b32 v170, v167, v169
	v_add_u32_e32 v161, 0xc00, v174
	s_waitcnt lgkmcnt(0)
	v_add_f32_e32 v169, v169, v170
	s_and_saveexec_b64 s[2:3], s[6:7]
	global_store_dword v161, v169, s[14:15]
	s_or_b64 exec, exec, s[2:3]
	s_waitcnt vmcnt(33)
	v_pk_fma_f32 v[78:79], v[78:79], 0.5, v[204:205] op_sel_hi:[1,0,1]
	v_pk_fma_f32 v[80:81], v[80:81], 0.5, v[206:207] op_sel_hi:[1,0,1]
	v_pk_fma_f32 v[74:75], v[74:75], 0.5, v[208:209] op_sel_hi:[1,0,1]
	v_pk_fma_f32 v[76:77], v[76:77], 0.5, v[210:211] op_sel_hi:[1,0,1]
	v_pk_fma_f32 v[70:71], v[70:71], 0.5, v[212:213] op_sel_hi:[1,0,1]
	v_pk_fma_f32 v[72:73], v[72:73], 0.5, v[214:215] op_sel_hi:[1,0,1]
	v_pk_fma_f32 v[66:67], v[66:67], 0.5, v[216:217] op_sel_hi:[1,0,1]
	v_pk_fma_f32 v[68:69], v[68:69], 0.5, v[218:219] op_sel_hi:[1,0,1]
	v_add_u32_e32 v159, 0x80000, v156
	global_store_dwordx4 v159, v[78:81], s[12:13]
	global_store_dwordx4 v159, v[74:77], s[12:13] offset:16
	global_store_dwordx4 v159, v[70:73], s[12:13] offset:512
	global_store_dwordx4 v159, v[66:69], s[12:13] offset:528
	v_mul_f32_e32 v169, v81, v81
	v_mul_f32_e32 v168, v79, v79
	v_fmac_f32_e32 v168, v78, v78
	v_fmac_f32_e32 v169, v80, v80
	v_add_f32_e32 v168, v168, v169
	v_mul_f32_e32 v169, v75, v75
	v_fmac_f32_e32 v169, v74, v74
	v_add_f32_e32 v168, v169, v168
	v_mul_f32_e32 v169, v77, v77
	v_fmac_f32_e32 v169, v76, v76
	v_add_f32_e32 v170, v169, v168
	v_mul_f32_e32 v169, v73, v73
	v_mul_f32_e32 v168, v71, v71
	v_fmac_f32_e32 v168, v70, v70
	v_fmac_f32_e32 v169, v72, v72
	v_add_f32_e32 v168, v168, v169
	v_mul_f32_e32 v169, v67, v67
	v_fmac_f32_e32 v169, v66, v66
	v_add_f32_e32 v168, v169, v168
	v_mul_f32_e32 v169, v69, v69
	v_fmac_f32_e32 v169, v68, v68
	v_add_f32_e32 v168, v169, v168
	v_add_f32_e32 v168, v170, v168
	ds_bpermute_b32 v169, v166, v168
	v_pk_mul_f32 v[78:79], v[54:55], v[78:79]
	v_pk_mul_f32 v[80:81], v[56:57], v[80:81]
	v_pk_mul_f32 v[74:75], v[50:51], v[74:75]
	v_pk_mul_f32 v[76:77], v[52:53], v[76:77]
	v_cvt_pk_bf16_f32 v78, v78, v79
	v_cvt_pk_bf16_f32 v79, v80, v81
	v_cvt_pk_bf16_f32 v80, v74, v75
	v_cvt_pk_bf16_f32 v81, v76, v77
	v_pk_mul_f32 v[70:71], v[30:31], v[70:71]
	v_pk_mul_f32 v[72:73], v[32:33], v[72:73]
	v_pk_mul_f32 v[66:67], v[26:27], v[66:67]
	v_pk_mul_f32 v[68:69], v[28:29], v[68:69]
	v_cvt_pk_bf16_f32 v70, v70, v71
	v_cvt_pk_bf16_f32 v71, v72, v73
	v_cvt_pk_bf16_f32 v72, v66, v67
	v_cvt_pk_bf16_f32 v73, v68, v69
	v_add_u32_e32 v160, 0x40000, v184
	v_add_u32_e32 v185, 0x8000, v160
	global_store_dwordx4 v160, v[78:81], s[18:19]
	global_store_dwordx4 v185, v[70:73], s[18:19]
	s_waitcnt lgkmcnt(0)
	v_add_f32_e32 v169, v168, v169
	ds_bpermute_b32 v170, v167, v169
	v_add_u32_e32 v161, 0x2000, v174
	s_waitcnt lgkmcnt(0)
	v_add_f32_e32 v169, v169, v170
	s_and_saveexec_b64 s[2:3], s[6:7]
	global_store_dword v161, v169, s[14:15]
	s_or_b64 exec, exec, s[2:3]
	s_waitcnt vmcnt(29)
	v_pk_fma_f32 v[62:63], v[62:63], 0.5, v[126:127] op_sel_hi:[1,0,1]
	v_pk_fma_f32 v[64:65], v[64:65], 0.5, v[128:129] op_sel_hi:[1,0,1]
	v_pk_fma_f32 v[58:59], v[58:59], 0.5, v[122:123] op_sel_hi:[1,0,1]
	v_pk_fma_f32 v[60:61], v[60:61], 0.5, v[124:125] op_sel_hi:[1,0,1]
	v_pk_fma_f32 v[46:47], v[46:47], 0.5, v[118:119] op_sel_hi:[1,0,1]
	v_pk_fma_f32 v[48:49], v[48:49], 0.5, v[120:121] op_sel_hi:[1,0,1]
	v_pk_fma_f32 v[42:43], v[42:43], 0.5, v[114:115] op_sel_hi:[1,0,1]
	v_pk_fma_f32 v[44:45], v[44:45], 0.5, v[116:117] op_sel_hi:[1,0,1]
	v_add_u32_e32 v159, 0x90000, v156
	global_store_dwordx4 v159, v[62:65], s[12:13]
	global_store_dwordx4 v159, v[58:61], s[12:13] offset:16
	global_store_dwordx4 v159, v[46:49], s[12:13] offset:512
	global_store_dwordx4 v159, v[42:45], s[12:13] offset:528
	v_mul_f32_e32 v169, v65, v65
	v_mul_f32_e32 v168, v63, v63
	v_fmac_f32_e32 v168, v62, v62
	v_fmac_f32_e32 v169, v64, v64
	v_add_f32_e32 v168, v168, v169
	v_mul_f32_e32 v169, v59, v59
	v_fmac_f32_e32 v169, v58, v58
	v_add_f32_e32 v168, v169, v168
	v_mul_f32_e32 v169, v61, v61
	v_fmac_f32_e32 v169, v60, v60
	v_add_f32_e32 v170, v169, v168
	v_mul_f32_e32 v169, v49, v49
	v_mul_f32_e32 v168, v47, v47
	v_fmac_f32_e32 v168, v46, v46
	v_fmac_f32_e32 v169, v48, v48
	v_add_f32_e32 v168, v168, v169
	v_mul_f32_e32 v169, v43, v43
	v_fmac_f32_e32 v169, v42, v42
	v_add_f32_e32 v168, v169, v168
	v_mul_f32_e32 v169, v45, v45
	v_fmac_f32_e32 v169, v44, v44
	v_add_f32_e32 v168, v169, v168
	v_add_f32_e32 v168, v170, v168
	ds_bpermute_b32 v169, v166, v168
	v_pk_mul_f32 v[62:63], v[54:55], v[62:63]
	v_pk_mul_f32 v[64:65], v[56:57], v[64:65]
	v_pk_mul_f32 v[58:59], v[50:51], v[58:59]
	v_pk_mul_f32 v[60:61], v[52:53], v[60:61]
	v_cvt_pk_bf16_f32 v62, v62, v63
	v_cvt_pk_bf16_f32 v63, v64, v65
	v_cvt_pk_bf16_f32 v64, v58, v59
	v_cvt_pk_bf16_f32 v65, v60, v61
	v_pk_mul_f32 v[46:47], v[30:31], v[46:47]
	v_pk_mul_f32 v[48:49], v[32:33], v[48:49]
	v_pk_mul_f32 v[42:43], v[26:27], v[42:43]
	v_pk_mul_f32 v[44:45], v[28:29], v[44:45]
	v_cvt_pk_bf16_f32 v46, v46, v47
	v_cvt_pk_bf16_f32 v47, v48, v49
	v_cvt_pk_bf16_f32 v48, v42, v43
	v_cvt_pk_bf16_f32 v49, v44, v45
	v_add_u32_e32 v160, 0x40800, v184
	v_add_u32_e32 v185, 0x8000, v160
	global_store_dwordx4 v160, v[62:65], s[18:19]
	global_store_dwordx4 v185, v[46:49], s[18:19]
	s_waitcnt lgkmcnt(0)
	v_add_f32_e32 v169, v168, v169
	ds_bpermute_b32 v170, v167, v169
	v_add_u32_e32 v161, 0x2400, v174
	s_waitcnt lgkmcnt(0)
	v_add_f32_e32 v169, v169, v170
	s_and_saveexec_b64 s[2:3], s[6:7]
	global_store_dword v161, v169, s[14:15]
	s_or_b64 exec, exec, s[2:3]
	s_waitcnt vmcnt(32)
	v_pk_fma_f32 v[38:39], v[38:39], 0.5, v[188:189] op_sel_hi:[1,0,1]
	v_pk_fma_f32 v[40:41], v[40:41], 0.5, v[190:191] op_sel_hi:[1,0,1]
	v_pk_fma_f32 v[34:35], v[34:35], 0.5, v[192:193] op_sel_hi:[1,0,1]
	v_pk_fma_f32 v[36:37], v[36:37], 0.5, v[194:195] op_sel_hi:[1,0,1]
	v_pk_fma_f32 v[22:23], v[22:23], 0.5, v[196:197] op_sel_hi:[1,0,1]
	v_pk_fma_f32 v[24:25], v[24:25], 0.5, v[198:199] op_sel_hi:[1,0,1]
	v_pk_fma_f32 v[18:19], v[18:19], 0.5, v[200:201] op_sel_hi:[1,0,1]
	v_pk_fma_f32 v[20:21], v[20:21], 0.5, v[202:203] op_sel_hi:[1,0,1]
	v_add_u32_e32 v159, 0xa0000, v156
	global_store_dwordx4 v159, v[38:41], s[12:13]
	global_store_dwordx4 v159, v[34:37], s[12:13] offset:16
	global_store_dwordx4 v159, v[22:25], s[12:13] offset:512
	global_store_dwordx4 v159, v[18:21], s[12:13] offset:528
	v_mul_f32_e32 v169, v41, v41
	v_mul_f32_e32 v168, v39, v39
	v_fmac_f32_e32 v168, v38, v38
	v_fmac_f32_e32 v169, v40, v40
	v_add_f32_e32 v168, v168, v169
	v_mul_f32_e32 v169, v35, v35
	v_fmac_f32_e32 v169, v34, v34
	v_add_f32_e32 v168, v169, v168
	v_mul_f32_e32 v169, v37, v37
	v_fmac_f32_e32 v169, v36, v36
	v_add_f32_e32 v170, v169, v168
	v_mul_f32_e32 v169, v25, v25
	v_mul_f32_e32 v168, v23, v23
	v_fmac_f32_e32 v168, v22, v22
	v_fmac_f32_e32 v169, v24, v24
	v_add_f32_e32 v168, v168, v169
	v_mul_f32_e32 v169, v19, v19
	v_fmac_f32_e32 v169, v18, v18
	v_add_f32_e32 v168, v169, v168
	v_mul_f32_e32 v169, v21, v21
	v_fmac_f32_e32 v169, v20, v20
	v_add_f32_e32 v168, v169, v168
	v_add_f32_e32 v168, v170, v168
	ds_bpermute_b32 v169, v166, v168
	v_pk_mul_f32 v[38:39], v[54:55], v[38:39]
	v_pk_mul_f32 v[40:41], v[56:57], v[40:41]
	v_pk_mul_f32 v[34:35], v[50:51], v[34:35]
	v_pk_mul_f32 v[36:37], v[52:53], v[36:37]
	v_cvt_pk_bf16_f32 v38, v38, v39
	v_cvt_pk_bf16_f32 v39, v40, v41
	v_cvt_pk_bf16_f32 v40, v34, v35
	v_cvt_pk_bf16_f32 v41, v36, v37
	v_pk_mul_f32 v[22:23], v[30:31], v[22:23]
	v_pk_mul_f32 v[24:25], v[32:33], v[24:25]
	v_pk_mul_f32 v[18:19], v[26:27], v[18:19]
	v_pk_mul_f32 v[20:21], v[28:29], v[20:21]
	v_cvt_pk_bf16_f32 v22, v22, v23
	v_cvt_pk_bf16_f32 v23, v24, v25
	v_cvt_pk_bf16_f32 v24, v18, v19
	v_cvt_pk_bf16_f32 v25, v20, v21
	v_add_u32_e32 v160, 0x41000, v184
	v_add_u32_e32 v185, 0x8000, v160
	global_store_dwordx4 v160, v[38:41], s[18:19]
	global_store_dwordx4 v185, v[22:25], s[18:19]
	s_waitcnt lgkmcnt(0)
	v_add_f32_e32 v169, v168, v169
	ds_bpermute_b32 v170, v167, v169
	v_add_u32_e32 v161, 0x2800, v174
	s_waitcnt lgkmcnt(0)
	v_add_f32_e32 v169, v169, v170
	s_and_saveexec_b64 s[2:3], s[6:7]
	global_store_dword v161, v169, s[14:15]
	s_or_b64 exec, exec, s[2:3]
	s_waitcnt vmcnt(28)
	v_pk_fma_f32 v[14:15], v[14:15], 0.5, v[110:111] op_sel_hi:[1,0,1]
	v_pk_fma_f32 v[16:17], v[16:17], 0.5, v[112:113] op_sel_hi:[1,0,1]
	v_pk_fma_f32 v[10:11], v[10:11], 0.5, v[106:107] op_sel_hi:[1,0,1]
	v_pk_fma_f32 v[12:13], v[12:13], 0.5, v[108:109] op_sel_hi:[1,0,1]
	v_pk_fma_f32 v[6:7], v[6:7], 0.5, v[102:103] op_sel_hi:[1,0,1]
	v_pk_fma_f32 v[8:9], v[8:9], 0.5, v[104:105] op_sel_hi:[1,0,1]
	v_pk_fma_f32 v[2:3], v[2:3], 0.5, v[98:99] op_sel_hi:[1,0,1]
	v_pk_fma_f32 v[4:5], v[4:5], 0.5, v[100:101] op_sel_hi:[1,0,1]
	v_add_u32_e32 v159, 0xb0000, v156
	global_store_dwordx4 v159, v[14:17], s[12:13]
	global_store_dwordx4 v159, v[10:13], s[12:13] offset:16
	global_store_dwordx4 v159, v[6:9], s[12:13] offset:512
	global_store_dwordx4 v159, v[2:5], s[12:13] offset:528
	v_mul_f32_e32 v169, v17, v17
	v_mul_f32_e32 v168, v15, v15
	v_fmac_f32_e32 v168, v14, v14
	v_fmac_f32_e32 v169, v16, v16
	v_add_f32_e32 v168, v168, v169
	v_mul_f32_e32 v169, v11, v11
	v_fmac_f32_e32 v169, v10, v10
	v_add_f32_e32 v168, v169, v168
	v_mul_f32_e32 v169, v13, v13
	v_fmac_f32_e32 v169, v12, v12
	v_add_f32_e32 v170, v169, v168
	v_mul_f32_e32 v169, v9, v9
	v_mul_f32_e32 v168, v7, v7
	v_fmac_f32_e32 v168, v6, v6
	v_fmac_f32_e32 v169, v8, v8
	v_add_f32_e32 v168, v168, v169
	v_mul_f32_e32 v169, v3, v3
	v_fmac_f32_e32 v169, v2, v2
	v_add_f32_e32 v168, v169, v168
	v_mul_f32_e32 v169, v5, v5
	v_fmac_f32_e32 v169, v4, v4
	v_add_f32_e32 v168, v169, v168
	v_add_f32_e32 v168, v170, v168
	ds_bpermute_b32 v169, v166, v168
	v_pk_mul_f32 v[14:15], v[54:55], v[14:15]
	v_pk_mul_f32 v[16:17], v[56:57], v[16:17]
	v_pk_mul_f32 v[10:11], v[50:51], v[10:11]
	v_pk_mul_f32 v[12:13], v[52:53], v[12:13]
	v_cvt_pk_bf16_f32 v14, v14, v15
	v_cvt_pk_bf16_f32 v15, v16, v17
	v_cvt_pk_bf16_f32 v16, v10, v11
	v_cvt_pk_bf16_f32 v17, v12, v13
	v_pk_mul_f32 v[6:7], v[30:31], v[6:7]
	v_pk_mul_f32 v[8:9], v[32:33], v[8:9]
	v_pk_mul_f32 v[2:3], v[26:27], v[2:3]
	v_pk_mul_f32 v[4:5], v[28:29], v[4:5]
	v_cvt_pk_bf16_f32 v6, v6, v7
	v_cvt_pk_bf16_f32 v7, v8, v9
	v_cvt_pk_bf16_f32 v8, v2, v3
	v_cvt_pk_bf16_f32 v9, v4, v5
	v_add_u32_e32 v160, 0x41800, v184
	v_add_u32_e32 v185, 0x8000, v160
	global_store_dwordx4 v160, v[14:17], s[18:19]
	global_store_dwordx4 v185, v[6:9], s[18:19]
	s_waitcnt lgkmcnt(0)
	v_add_f32_e32 v169, v168, v169
	ds_bpermute_b32 v170, v167, v169
	v_add_u32_e32 v161, 0x2c00, v174
	s_waitcnt lgkmcnt(0)
	v_add_f32_e32 v169, v169, v170
	s_and_saveexec_b64 s[2:3], s[6:7]
	global_store_dword v161, v169, s[14:15]
	s_or_b64 exec, exec, s[2:3]
	s_and_b64 vcc, exec, s[8:9]
	s_mov_b64 s[2:3], -1
	s_cbranch_vccnz .LBB0_453
	s_andn2_b64 vcc, exec, s[4:5]
	s_cbranch_vccnz .LBB0_452
	s_barrier
	s_branch .LBB0_452

.LBB0_540:
	s_or_b64 exec, exec, s[0:1]
	s_waitcnt lgkmcnt(0)
	s_barrier
	v_readlane_b32 s2, v254, 8
	s_mov_b64 s[0:1], s[70:71]
	v_mov_b32_e32 v0, v220
	v_mov_b32_e32 v10, v220
	v_readlane_b32 s3, v254, 9
	s_andn2_b64 vcc, exec, s[2:3]
	v_readfirstlane_b32 s4, v10
	s_cbranch_vccnz .LBB0_572
	v_lshlrev_b32_e32 v0, 4, v10
	v_add_u32_e32 v2, 0x2000, v0
	v_ashrrev_i32_e32 v3, 31, v2
	v_lshrrev_b32_e32 v3, 22, v3
	v_add_u32_e32 v3, v2, v3
	v_ashrrev_i32_e32 v11, 10, v3
	s_load_dwordx2 s[8:9], s[0:1], 0x98
	v_mul_i32_i24_e32 v3, 0x400, v11
	v_sub_u32_e32 v2, v2, v3
	v_lshrrev_b32_e32 v3, 4, v2
	v_bitop3_b32 v2, v3, v2, 32 bitop3:0x6c
	v_ashrrev_i32_e32 v3, 31, v2
	s_waitcnt lgkmcnt(0)
	s_add_u32 s26, s8, 0x10600000
	v_lshrrev_b32_e32 v3, 26, v3
	s_addc_u32 s27, s9, 0
	s_mul_i32 s0, s48, 0x2b00000
	v_add_u32_e32 v3, v2, v3
	v_lshlrev_b32_e32 v4, 3, v11
	s_add_u32 s0, s8, s0
	v_ashrrev_i32_e32 v12, 6, v3
	v_and_b32_e32 v4, -16, v4
	s_addc_u32 s1, s9, 0
	v_add_u32_e32 v4, v12, v4
	s_add_u32 s28, s0, 0x1080000
	v_and_b32_e32 v5, 3, v12
	s_mov_b32 s0, 0x1fffe0
	v_lshrrev_b32_e32 v6, 2, v4
	v_lshlrev_b32_e32 v7, 1, v4
	v_and_or_b32 v5, v4, s0, v5
	v_and_b32_e32 v6, 4, v6
	v_and_b32_e32 v7, 24, v7
	v_and_b32_e32 v3, 0xc0, v3
	v_or3_b32 v5, v5, v6, v7
	v_sub_u32_e32 v2, v2, v3
	v_mov_b32_e32 v7, 1
	v_lshlrev_b32_e32 v6, 5, v11
	v_ashrrev_i16_sdwa v2, v7, sext(v2) dst_sel:DWORD dst_unused:UNUSED_PAD src0_sel:DWORD src1_sel:BYTE_0
	v_and_b32_e32 v6, 32, v6
	v_bfe_i32 v13, v2, 0, 16
	v_add_lshl_u32 v2, v6, v13, 1
	s_waitcnt vmcnt(16)
	v_lshl_add_u32 v158, v5, 11, v2
	v_lshlrev_b32_e32 v160, 4, v220
	v_add_u32_e32 v160, 0x2000, v160
	v_bfe_i32 v2, v10, 27, 1
	v_lshrrev_b32_e32 v2, 22, v2
	v_add_u32_e32 v2, v0, v2
	v_and_b32_e32 v2, 0xfffffc00, v2
	v_sub_u32_e32 v0, v0, v2
	v_lshrrev_b32_e32 v2, 4, v0
	v_ashrrev_i32_e32 v3, 31, v10
	v_bitop3_b32 v0, v2, v0, 32 bitop3:0x6c
	v_lshrrev_b32_e32 v3, 26, v3
	v_ashrrev_i32_e32 v2, 31, v0
	v_add_u32_e32 v3, v10, v3
	v_lshrrev_b32_e32 v2, 26, v2
	v_ashrrev_i32_e32 v15, 6, v3
	v_add_u32_e32 v2, v0, v2
	v_lshlrev_b32_e32 v3, 3, v15
	v_ashrrev_i32_e32 v14, 6, v2
	v_and_b32_e32 v3, -16, v3
	v_add_u32_e32 v3, v14, v3
	v_and_b32_e32 v4, 3, v14
	v_lshrrev_b32_e32 v5, 2, v3
	v_lshlrev_b32_e32 v6, 1, v3
	v_and_b32_e32 v2, 0xc0, v2
	s_addc_u32 s29, s1, 0
	s_ashr_i32 s6, s4, 6
	v_and_or_b32 v4, v3, s0, v4
	v_and_b32_e32 v5, 4, v5
	v_and_b32_e32 v6, 24, v6
	v_sub_u32_e32 v0, v0, v2
	s_ashr_i32 s5, s4, 8
	s_lshl_b32 s30, s6, 10
	v_or3_b32 v4, v4, v5, v6
	v_lshlrev_b32_e32 v5, 5, v15
	v_ashrrev_i16_sdwa v0, v7, sext(v0) dst_sel:DWORD dst_unused:UNUSED_PAD src0_sel:DWORD src1_sel:BYTE_0
	v_readlane_b32 s0, v254, 53
	v_and_b32_e32 v5, 32, v5
	v_bfe_i32 v16, v0, 0, 16
	v_readlane_b32 s1, v254, 54
	s_add_u32 s22, s28, s0
	v_add_lshl_u32 v2, v5, v16, 1
	s_addc_u32 s23, s29, s1
	s_add_i32 s31, s30, 0
	v_lshl_add_u32 v0, v4, 11, v2
	s_add_i32 m0, s31, 0x10000
	v_lshlrev_b32_e32 v162, 4, v220
	global_load_lds_dwordx4 v0, s[22:23]
	s_add_i32 m0, s31, 0x12000
	s_add_u32 s0, s22, 0x40000
	global_load_lds_dwordx4 v158, s[22:23]
	s_addc_u32 s1, s23, 0
	s_add_i32 m0, s31, 0x14000
	v_mov_b32_e32 v159, v1
	global_load_lds_dwordx4 v0, s[0:1]
	s_add_i32 m0, s31, 0x16000
	v_mov_b32_e32 v163, v1
	global_load_lds_dwordx4 v158, s[0:1]
	v_readlane_b32 s0, v255, 3
	v_readlane_b32 s1, v255, 4
	s_add_u32 s10, s26, s0
	s_addc_u32 s11, s27, s1
	s_add_i32 s34, s31, 0x2000
	s_mov_b32 m0, s31
	s_add_u32 s0, s10, 0x40000
	global_load_lds_dwordx4 v162, s[10:11]
	s_mov_b32 m0, s34
	s_addc_u32 s1, s11, 0
	s_add_i32 s35, s31, 0x4000
	global_load_lds_dwordx4 v160, s[10:11]
	s_mov_b32 m0, s35
	s_add_i32 s36, s31, 0x6000
	global_load_lds_dwordx4 v162, s[0:1]
	s_mov_b32 m0, s36
	v_mov_b32_e32 v161, v1
	global_load_lds_dwordx4 v160, s[0:1]
	s_cmp_eq_u32 s5, 1
	v_mov_b32_e32 v221, 0x3ecc95a3
	v_lshl_add_u64 v[8:9], s[22:23], 0, v[0:1]
	v_lshl_add_u64 v[6:7], s[22:23], 0, v[158:159]
	v_lshl_add_u64 v[2:3], s[10:11], 0, v[162:163]
	s_cselect_b64 s[0:1], -1, 0
	s_cmp_lg_u32 s5, 1
	v_lshl_add_u64 v[4:5], s[10:11], 0, v[160:161]
	s_cbranch_scc1 .LBB0_543
	s_barrier
.LBB0_543:
	s_add_u32 s2, s8, 0x5600000
	s_addc_u32 s3, s9, 0
	s_and_b32 s16, s6, 3
	s_add_i32 m0, s31, 0x18000
	v_lshl_add_u64 v[8:9], v[8:9], 0, s[78:79]
	s_lshl_b32 s12, s5, 13
	s_lshl_b32 s13, s16, 12
	s_waitcnt vmcnt(2)
	s_barrier
	global_load_lds_dwordx4 v[8:9], off
	v_lshl_add_u64 v[6:7], v[6:7], 0, s[78:79]
	s_add_i32 m0, s31, 0x1a000
	s_add_i32 s37, s31, 0x8000
	s_add_i32 s38, s31, 0xa000
	global_load_lds_dwordx4 v[6:7], off
	s_mov_b64 s[50:51], 0x4000
	v_lshl_add_u64 v[2:3], v[2:3], 0, s[50:51]
	s_mov_b32 m0, s37
	s_add_u32 s6, s22, 0x40080
	global_load_lds_dwordx4 v[2:3], off
	v_lshl_add_u64 v[2:3], v[4:5], 0, s[50:51]
	s_mov_b32 m0, s38
	s_addc_u32 s7, s23, 0
	global_load_lds_dwordx4 v[2:3], off
	s_add_i32 m0, s31, 0x1c000
	v_lshl_add_u64 v[2:3], s[6:7], 0, v[0:1]
	global_load_lds_dwordx4 v[2:3], off
	v_lshl_add_u64 v[2:3], s[6:7], 0, v[158:159]
	s_add_i32 m0, s31, 0x1e000
	v_bfe_u32 v4, v10, 4, 2
	global_load_lds_dwordx4 v[2:3], off
	v_and_b32_e32 v3, 15, v10
	v_lshlrev_b32_e32 v2, 4, v4
	v_lshlrev_b32_e32 v5, 2, v10
	v_lshl_or_b32 v173, s5, 6, v3
	v_lshl_or_b32 v3, v3, 6, v2
	v_and_b32_e32 v5, 32, v5
	v_lshlrev_b32_e32 v6, 3, v4
	v_bitop3_b32 v7, v3, s12, v5 bitop3:0xde
	v_bitop3_b32 v183, v3, s13, v5 bitop3:0xde
	v_cmp_gt_u32_e64 s[6:7], 2, v4
	v_lshlrev_b32_e32 v4, 5, v4
	v_mov_b32_e32 v5, v1
	v_mov_b32_e32 v3, v1
	v_lshl_add_u64 v[4:5], s[8:9], 0, v[4:5]
	v_lshl_add_u64 v[2:3], s[8:9], 0, v[2:3]
	s_mov_b64 s[8:9], 0x1d600000
	v_lshl_add_u64 v[166:167], v[2:3], 0, s[8:9]
	v_lshlrev_b32_e32 v2, 14, v15
	v_and_b32_e32 v2, 0xffff8000, v2
	v_lshl_add_u32 v2, v14, 11, v2
	v_and_b32_e32 v3, 1, v15
	v_lshl_or_b32 v2, v3, 6, v2
	v_lshlrev_b32_e32 v168, 4, v220
	v_lshlrev_b32_e32 v2, 14, v11
	v_and_b32_e32 v2, 0xffff8000, v2
	s_waitcnt vmcnt(6)
	s_cmpk_lt_u32 s4, 0x100
	v_lshl_add_u32 v2, v12, 11, v2
	v_and_b32_e32 v3, 1, v11
	s_cselect_b64 s[4:5], -1, 0
	s_cmp_eq_u32 s16, 0
	s_mov_b64 s[14:15], 0x1d800000
	v_lshl_or_b32 v2, v3, 6, v2
	v_readlane_b32 s8, v255, 1
	s_mov_b32 s39, 0
	s_cselect_b64 s[12:13], -1, 0
	v_lshl_add_u64 v[164:165], v[4:5], 0, s[14:15]
	v_lshl_or_b32 v225, s16, 5, v6
	v_mov_b32_e32 v169, v1
	v_lshlrev_b32_e32 v184, 4, v220
	v_add_u32_e32 v184, 0x2000, v184
	v_mov_b32_e32 v185, v1
	v_add_u32_e32 v227, 0, v7
	v_readlane_b32 s40, v254, 48
	s_mov_b32 s41, s8
	s_barrier
	v_readlane_b32 s9, v255, 2
	s_branch .LBB0_546

.LBB0_548:
	s_ashr_i32 s17, s16, 31
	s_lshl_b64 s[18:19], s[16:17], 19
	s_add_u32 s18, s26, s18
	s_addc_u32 s19, s27, s19
	s_and_b64 s[20:21], s[8:9], exec
	s_cselect_b32 s17, s19, s11
	s_cselect_b32 s42, s18, s10
	s_ashr_i32 s15, s14, 31
	s_lshl_b64 s[20:21], s[14:15], 19
	s_add_u32 s20, s28, s20
	s_addc_u32 s21, s29, s21
	s_and_b64 s[24:25], s[8:9], exec
	s_cselect_b32 s15, s21, s23
	s_cselect_b32 s43, s20, s22
	s_add_u32 s10, s10, 0x44000
	s_addc_u32 s11, s11, 0
	s_add_u32 s44, s22, 0x100
	v_mov_b32_e32 v2, 0
	s_addc_u32 s45, s23, 0
	s_mov_b32 s46, -2
	v_mov_b32_e32 v3, v2
	v_mov_b32_e32 v4, v2
	v_mov_b32_e32 v5, v2
	v_mov_b32_e32 v6, v2
	v_mov_b32_e32 v7, v2
	v_mov_b32_e32 v8, v2
	v_mov_b32_e32 v9, v2
	v_mov_b32_e32 v18, v2
	v_mov_b32_e32 v19, v2
	v_mov_b32_e32 v20, v2
	v_mov_b32_e32 v21, v2
	v_mov_b32_e32 v22, v2
	v_mov_b32_e32 v23, v2
	v_mov_b32_e32 v24, v2
	v_mov_b32_e32 v25, v2
	v_mov_b32_e32 v34, v2
	v_mov_b32_e32 v35, v2
	v_mov_b32_e32 v36, v2
	v_mov_b32_e32 v37, v2
	v_mov_b32_e32 v38, v2
	v_mov_b32_e32 v39, v2
	v_mov_b32_e32 v40, v2
	v_mov_b32_e32 v41, v2
	s_waitcnt vmcnt(0)
	v_mov_b32_e32 v50, v2
	v_mov_b32_e32 v51, v2
	v_mov_b32_e32 v52, v2
	v_mov_b32_e32 v53, v2
	v_mov_b32_e32 v54, v2
	v_mov_b32_e32 v55, v2
	v_mov_b32_e32 v56, v2
	v_mov_b32_e32 v57, v2
	v_mov_b32_e32 v10, v2
	v_mov_b32_e32 v11, v2
	v_mov_b32_e32 v12, v2
	v_mov_b32_e32 v13, v2
	v_mov_b32_e32 v14, v2
	v_mov_b32_e32 v15, v2
	v_mov_b32_e32 v16, v2
	v_mov_b32_e32 v17, v2
	v_mov_b32_e32 v26, v2
	v_mov_b32_e32 v27, v2
	v_mov_b32_e32 v28, v2
	v_mov_b32_e32 v29, v2
	v_mov_b32_e32 v30, v2
	v_mov_b32_e32 v31, v2
	v_mov_b32_e32 v32, v2
	v_mov_b32_e32 v33, v2
	v_mov_b32_e32 v42, v2
	v_mov_b32_e32 v43, v2
	v_mov_b32_e32 v44, v2
	v_mov_b32_e32 v45, v2
	v_mov_b32_e32 v46, v2
	v_mov_b32_e32 v47, v2
	v_mov_b32_e32 v48, v2
	v_mov_b32_e32 v49, v2
	v_mov_b32_e32 v58, v2
	v_mov_b32_e32 v59, v2
	v_mov_b32_e32 v60, v2
	v_mov_b32_e32 v61, v2
	v_mov_b32_e32 v62, v2
	v_mov_b32_e32 v63, v2
	v_mov_b32_e32 v64, v2
	v_mov_b32_e32 v65, v2
	v_mov_b32_e32 v66, v2
	v_mov_b32_e32 v67, v2
	v_mov_b32_e32 v68, v2
	v_mov_b32_e32 v69, v2
	v_mov_b32_e32 v70, v2
	v_mov_b32_e32 v71, v2
	v_mov_b32_e32 v72, v2
	v_mov_b32_e32 v73, v2
	v_mov_b32_e32 v82, v2
	v_mov_b32_e32 v83, v2
	v_mov_b32_e32 v84, v2
	v_mov_b32_e32 v85, v2
	v_mov_b32_e32 v86, v2
	v_mov_b32_e32 v87, v2
	v_mov_b32_e32 v88, v2
	v_mov_b32_e32 v89, v2
	v_mov_b32_e32 v98, v2
	v_mov_b32_e32 v99, v2
	v_mov_b32_e32 v100, v2
	v_mov_b32_e32 v101, v2
	v_mov_b32_e32 v102, v2
	v_mov_b32_e32 v103, v2
	v_mov_b32_e32 v104, v2
	v_mov_b32_e32 v105, v2
	v_mov_b32_e32 v114, v2
	v_mov_b32_e32 v115, v2
	v_mov_b32_e32 v116, v2
	v_mov_b32_e32 v117, v2
	v_mov_b32_e32 v118, v2
	v_mov_b32_e32 v119, v2
	v_mov_b32_e32 v120, v2
	v_mov_b32_e32 v121, v2
	v_mov_b32_e32 v74, v2
	v_mov_b32_e32 v75, v2
	v_mov_b32_e32 v76, v2
	v_mov_b32_e32 v77, v2
	v_mov_b32_e32 v78, v2
	v_mov_b32_e32 v79, v2
	v_mov_b32_e32 v80, v2
	v_mov_b32_e32 v81, v2
	v_mov_b32_e32 v90, v2
	v_mov_b32_e32 v91, v2
	v_mov_b32_e32 v92, v2
	v_mov_b32_e32 v93, v2
	v_mov_b32_e32 v94, v2
	v_mov_b32_e32 v95, v2
	v_mov_b32_e32 v96, v2
	v_mov_b32_e32 v97, v2
	v_mov_b32_e32 v106, v2
	v_mov_b32_e32 v107, v2
	v_mov_b32_e32 v108, v2
	v_mov_b32_e32 v109, v2
	v_mov_b32_e32 v110, v2
	v_mov_b32_e32 v111, v2
	v_mov_b32_e32 v112, v2
	v_mov_b32_e32 v113, v2
	v_mov_b32_e32 v122, v2
	v_mov_b32_e32 v123, v2
	v_mov_b32_e32 v124, v2
	v_mov_b32_e32 v125, v2
	v_mov_b32_e32 v126, v2
	v_mov_b32_e32 v127, v2
	v_mov_b32_e32 v128, v2
	v_mov_b32_e32 v129, v2
.LBB0_549:
	s_add_u32 s22, s10, 0xfffc4000
	s_addc_u32 s23, s11, -1
	s_add_i32 s47, 0, 0x10000
	s_cmp_eq_u32 s46, 12
	s_cselect_b32 s25, s17, s23
	s_cselect_b32 s24, s42, s22
	s_cselect_b32 s23, s15, s45
	s_cselect_b32 s22, s43, s44
	s_add_i32 s49, 0, 0x14000
	v_add_u32_e32 v142, s47, v183
	v_add_u32_e32 v170, s49, v183
	ds_read_b128 v[130:133], v142
	ds_read_b128 v[134:137], v142 offset:1024
	ds_read_b128 v[138:141], v142 offset:2048
	ds_read_b128 v[142:145], v142 offset:3072
	ds_read_b128 v[146:149], v170
	ds_read_b128 v[150:153], v170 offset:1024
	ds_read_b128 v[154:157], v170 offset:2048
	ds_read_b128 v[174:177], v170 offset:3072
	v_lshl_add_u64 v[218:219], s[10:11], 0, v[168:169]
	s_add_i32 m0, s31, 0xc000
	ds_read_b128 v[186:189], v227
	ds_read_b128 v[190:193], v227 offset:1024
	ds_read_b128 v[194:197], v227 offset:2048
	ds_read_b128 v[198:201], v227 offset:3072
	ds_read_b128 v[202:205], v227 offset:4096
	ds_read_b128 v[206:209], v227 offset:5120
	ds_read_b128 v[210:213], v227 offset:6144
	ds_read_b128 v[214:217], v227 offset:7168
	global_load_lds_dwordx4 v[218:219], off
	v_lshl_add_u64 v[218:219], s[10:11], 0, v[184:185]
	s_add_i32 m0, s31, 0xe000
	s_nop 0
	global_load_lds_dwordx4 v[218:219], off
	s_waitcnt vmcnt(8)
	s_waitcnt lgkmcnt(0)
	s_barrier
	s_setprio 1
	s_waitcnt lgkmcnt(0)
	v_mfma_f32_16x16x32_bf16 v[126:129], v[130:133], v[186:189], v[126:129]
	v_mfma_f32_16x16x32_bf16 v[122:125], v[138:141], v[186:189], v[122:125]
	v_mfma_f32_16x16x32_bf16 v[110:113], v[130:133], v[194:197], v[110:113]
	v_mfma_f32_16x16x32_bf16 v[106:109], v[138:141], v[194:197], v[106:109]
	v_mfma_f32_16x16x32_bf16 v[94:97], v[130:133], v[202:205], v[94:97]
	v_mfma_f32_16x16x32_bf16 v[90:93], v[138:141], v[202:205], v[90:93]
	v_mfma_f32_16x16x32_bf16 v[78:81], v[130:133], v[210:213], v[78:81]
	v_mfma_f32_16x16x32_bf16 v[74:77], v[138:141], v[210:213], v[74:77]
	v_mfma_f32_16x16x32_bf16 v[126:129], v[134:137], v[190:193], v[126:129]
	v_mfma_f32_16x16x32_bf16 v[122:125], v[142:145], v[190:193], v[122:125]
	v_mfma_f32_16x16x32_bf16 v[110:113], v[134:137], v[198:201], v[110:113]
	v_mfma_f32_16x16x32_bf16 v[106:109], v[142:145], v[198:201], v[106:109]
	v_mfma_f32_16x16x32_bf16 v[94:97], v[134:137], v[206:209], v[94:97]
	v_mfma_f32_16x16x32_bf16 v[90:93], v[142:145], v[206:209], v[90:93]
	v_mfma_f32_16x16x32_bf16 v[78:81], v[134:137], v[214:217], v[78:81]
	v_mfma_f32_16x16x32_bf16 v[74:77], v[142:145], v[214:217], v[74:77]
	s_setprio 0
	s_setprio 1
	v_mfma_f32_16x16x32_bf16 v[118:121], v[146:149], v[186:189], v[118:121]
	v_mfma_f32_16x16x32_bf16 v[114:117], v[154:157], v[186:189], v[114:117]
	v_mfma_f32_16x16x32_bf16 v[102:105], v[146:149], v[194:197], v[102:105]
	v_mfma_f32_16x16x32_bf16 v[98:101], v[154:157], v[194:197], v[98:101]
	v_mfma_f32_16x16x32_bf16 v[86:89], v[146:149], v[202:205], v[86:89]
	v_mfma_f32_16x16x32_bf16 v[82:85], v[154:157], v[202:205], v[82:85]
	v_mfma_f32_16x16x32_bf16 v[70:73], v[146:149], v[210:213], v[70:73]
	v_mfma_f32_16x16x32_bf16 v[66:69], v[154:157], v[210:213], v[66:69]
	v_mfma_f32_16x16x32_bf16 v[118:121], v[150:153], v[190:193], v[118:121]
	v_mfma_f32_16x16x32_bf16 v[114:117], v[174:177], v[190:193], v[114:117]
	v_mfma_f32_16x16x32_bf16 v[102:105], v[150:153], v[198:201], v[102:105]
	v_mfma_f32_16x16x32_bf16 v[98:101], v[174:177], v[198:201], v[98:101]
	v_mfma_f32_16x16x32_bf16 v[86:89], v[150:153], v[206:209], v[86:89]
	v_mfma_f32_16x16x32_bf16 v[82:85], v[174:177], v[206:209], v[82:85]
	v_mfma_f32_16x16x32_bf16 v[70:73], v[150:153], v[214:217], v[70:73]
	v_mfma_f32_16x16x32_bf16 v[66:69], v[174:177], v[214:217], v[66:69]
	s_setprio 0
	s_barrier
	s_add_i32 s47, s47, s30
	v_lshl_add_u64 v[218:219], s[22:23], 0, v[0:1]
	s_mov_b32 m0, s47
	ds_read_b128 v[186:189], v227 offset:16384
	ds_read_b128 v[190:193], v227 offset:17408
	ds_read_b128 v[194:197], v227 offset:18432
	ds_read_b128 v[198:201], v227 offset:19456
	ds_read_b128 v[202:205], v227 offset:20480
	ds_read_b128 v[206:209], v227 offset:21504
	ds_read_b128 v[210:213], v227 offset:22528
	ds_read_b128 v[214:217], v227 offset:23552
	global_load_lds_dwordx4 v[218:219], off
	s_add_i32 m0, s47, 0x2000
	s_add_u32 s50, s22, 0x40000
	v_lshl_add_u64 v[238:239], s[22:23], 0, v[158:159]
	s_addc_u32 s51, s23, 0
	s_add_i32 s47, s49, s30
	global_load_lds_dwordx4 v[238:239], off
	v_lshl_add_u64 v[240:241], s[50:51], 0, v[0:1]
	s_mov_b32 m0, s47
	v_lshl_add_u64 v[242:243], s[24:25], 0, v[160:161]
	global_load_lds_dwordx4 v[240:241], off
	v_lshl_add_u64 v[240:241], s[50:51], 0, v[158:159]
	s_add_i32 m0, s47, 0x2000
	s_nop 0
	global_load_lds_dwordx4 v[240:241], off
	v_lshl_add_u64 v[240:241], s[24:25], 0, v[162:163]
	s_mov_b32 m0, s31
	s_nop 0
	global_load_lds_dwordx4 v[240:241], off
	s_mov_b32 m0, s34
	s_nop 0
	global_load_lds_dwordx4 v[242:243], off
	s_waitcnt vmcnt(8)
	s_waitcnt lgkmcnt(0)
	s_barrier
	s_setprio 1
	s_waitcnt lgkmcnt(0)
	v_mfma_f32_16x16x32_bf16 v[62:65], v[130:133], v[186:189], v[62:65]
	v_mfma_f32_16x16x32_bf16 v[58:61], v[138:141], v[186:189], v[58:61]
	v_mfma_f32_16x16x32_bf16 v[46:49], v[130:133], v[194:197], v[46:49]
	v_mfma_f32_16x16x32_bf16 v[42:45], v[138:141], v[194:197], v[42:45]
	v_mfma_f32_16x16x32_bf16 v[30:33], v[130:133], v[202:205], v[30:33]
	v_mfma_f32_16x16x32_bf16 v[26:29], v[138:141], v[202:205], v[26:29]
	v_mfma_f32_16x16x32_bf16 v[14:17], v[130:133], v[210:213], v[14:17]
	v_mfma_f32_16x16x32_bf16 v[10:13], v[138:141], v[210:213], v[10:13]
	v_mfma_f32_16x16x32_bf16 v[62:65], v[134:137], v[190:193], v[62:65]
	v_mfma_f32_16x16x32_bf16 v[58:61], v[142:145], v[190:193], v[58:61]
	v_mfma_f32_16x16x32_bf16 v[46:49], v[134:137], v[198:201], v[46:49]
	v_mfma_f32_16x16x32_bf16 v[42:45], v[142:145], v[198:201], v[42:45]
	v_mfma_f32_16x16x32_bf16 v[30:33], v[134:137], v[206:209], v[30:33]
	v_mfma_f32_16x16x32_bf16 v[26:29], v[142:145], v[206:209], v[26:29]
	v_mfma_f32_16x16x32_bf16 v[14:17], v[134:137], v[214:217], v[14:17]
	v_mfma_f32_16x16x32_bf16 v[10:13], v[142:145], v[214:217], v[10:13]
	s_setprio 0
	s_setprio 1
	v_mfma_f32_16x16x32_bf16 v[54:57], v[146:149], v[186:189], v[54:57]
	v_mfma_f32_16x16x32_bf16 v[50:53], v[154:157], v[186:189], v[50:53]
	v_mfma_f32_16x16x32_bf16 v[38:41], v[146:149], v[194:197], v[38:41]
	v_mfma_f32_16x16x32_bf16 v[34:37], v[154:157], v[194:197], v[34:37]
	v_mfma_f32_16x16x32_bf16 v[22:25], v[146:149], v[202:205], v[22:25]
	v_mfma_f32_16x16x32_bf16 v[18:21], v[154:157], v[202:205], v[18:21]
	v_mfma_f32_16x16x32_bf16 v[6:9], v[146:149], v[210:213], v[6:9]
	v_mfma_f32_16x16x32_bf16 v[2:5], v[154:157], v[210:213], v[2:5]
	v_mfma_f32_16x16x32_bf16 v[54:57], v[150:153], v[190:193], v[54:57]
	v_mfma_f32_16x16x32_bf16 v[50:53], v[174:177], v[190:193], v[50:53]
	v_mfma_f32_16x16x32_bf16 v[38:41], v[150:153], v[198:201], v[38:41]
	v_mfma_f32_16x16x32_bf16 v[34:37], v[174:177], v[198:201], v[34:37]
	v_mfma_f32_16x16x32_bf16 v[22:25], v[150:153], v[206:209], v[22:25]
	v_mfma_f32_16x16x32_bf16 v[18:21], v[174:177], v[206:209], v[18:21]
	v_mfma_f32_16x16x32_bf16 v[6:9], v[150:153], v[214:217], v[6:9]
	v_mfma_f32_16x16x32_bf16 v[2:5], v[174:177], v[214:217], v[2:5]
	s_setprio 0
	s_barrier
	s_add_i32 s47, 0, 0x18000
	s_add_i32 s49, 0, 0x1c000
	v_add_u32_e32 v142, s47, v183
	v_add_u32_e32 v170, s49, v183
	ds_read_b128 v[130:133], v142
	ds_read_b128 v[134:137], v142 offset:1024
	ds_read_b128 v[138:141], v142 offset:2048
	ds_read_b128 v[142:145], v142 offset:3072
	ds_read_b128 v[146:149], v170
	ds_read_b128 v[150:153], v170 offset:1024
	ds_read_b128 v[154:157], v170 offset:2048
	ds_read_b128 v[174:177], v170 offset:3072
	s_add_u32 s24, s24, 0x40000
	s_addc_u32 s25, s25, 0
	s_mov_b32 m0, s35
	v_lshl_add_u64 v[244:245], s[24:25], 0, v[162:163]
	ds_read_b128 v[186:189], v227 offset:32768
	ds_read_b128 v[190:193], v227 offset:33792
	ds_read_b128 v[194:197], v227 offset:34816
	ds_read_b128 v[198:201], v227 offset:35840
	ds_read_b128 v[202:205], v227 offset:36864
	ds_read_b128 v[206:209], v227 offset:37888
	ds_read_b128 v[210:213], v227 offset:38912
	ds_read_b128 v[214:217], v227 offset:39936
	global_load_lds_dwordx4 v[244:245], off
	v_lshl_add_u64 v[244:245], s[24:25], 0, v[160:161]
	s_mov_b32 m0, s36
	s_nop 0
	global_load_lds_dwordx4 v[244:245], off
	s_waitcnt vmcnt(8)
	s_waitcnt lgkmcnt(0)
	s_barrier
	s_setprio 1
	s_waitcnt lgkmcnt(0)
	v_mfma_f32_16x16x32_bf16 v[126:129], v[130:133], v[186:189], v[126:129]
	v_mfma_f32_16x16x32_bf16 v[122:125], v[138:141], v[186:189], v[122:125]
	v_mfma_f32_16x16x32_bf16 v[110:113], v[130:133], v[194:197], v[110:113]
	v_mfma_f32_16x16x32_bf16 v[106:109], v[138:141], v[194:197], v[106:109]
	v_mfma_f32_16x16x32_bf16 v[94:97], v[130:133], v[202:205], v[94:97]
	v_mfma_f32_16x16x32_bf16 v[90:93], v[138:141], v[202:205], v[90:93]
	v_mfma_f32_16x16x32_bf16 v[78:81], v[130:133], v[210:213], v[78:81]
	v_mfma_f32_16x16x32_bf16 v[74:77], v[138:141], v[210:213], v[74:77]
	v_mfma_f32_16x16x32_bf16 v[126:129], v[134:137], v[190:193], v[126:129]
	v_mfma_f32_16x16x32_bf16 v[122:125], v[142:145], v[190:193], v[122:125]
	v_mfma_f32_16x16x32_bf16 v[110:113], v[134:137], v[198:201], v[110:113]
	v_mfma_f32_16x16x32_bf16 v[106:109], v[142:145], v[198:201], v[106:109]
	v_mfma_f32_16x16x32_bf16 v[94:97], v[134:137], v[206:209], v[94:97]
	v_mfma_f32_16x16x32_bf16 v[90:93], v[142:145], v[206:209], v[90:93]
	v_mfma_f32_16x16x32_bf16 v[78:81], v[134:137], v[214:217], v[78:81]
	v_mfma_f32_16x16x32_bf16 v[74:77], v[142:145], v[214:217], v[74:77]
	s_setprio 0
	s_setprio 1
	v_mfma_f32_16x16x32_bf16 v[118:121], v[146:149], v[186:189], v[118:121]
	v_mfma_f32_16x16x32_bf16 v[114:117], v[154:157], v[186:189], v[114:117]
	v_mfma_f32_16x16x32_bf16 v[102:105], v[146:149], v[194:197], v[102:105]
	v_mfma_f32_16x16x32_bf16 v[98:101], v[154:157], v[194:197], v[98:101]
	v_mfma_f32_16x16x32_bf16 v[86:89], v[146:149], v[202:205], v[86:89]
	v_mfma_f32_16x16x32_bf16 v[82:85], v[154:157], v[202:205], v[82:85]
	v_mfma_f32_16x16x32_bf16 v[70:73], v[146:149], v[210:213], v[70:73]
	v_mfma_f32_16x16x32_bf16 v[66:69], v[154:157], v[210:213], v[66:69]
	v_mfma_f32_16x16x32_bf16 v[118:121], v[150:153], v[190:193], v[118:121]
	v_mfma_f32_16x16x32_bf16 v[114:117], v[174:177], v[190:193], v[114:117]
	v_mfma_f32_16x16x32_bf16 v[102:105], v[150:153], v[198:201], v[102:105]
	v_mfma_f32_16x16x32_bf16 v[98:101], v[174:177], v[198:201], v[98:101]
	v_mfma_f32_16x16x32_bf16 v[86:89], v[150:153], v[206:209], v[86:89]
	v_mfma_f32_16x16x32_bf16 v[82:85], v[174:177], v[206:209], v[82:85]
	v_mfma_f32_16x16x32_bf16 v[70:73], v[150:153], v[214:217], v[70:73]
	v_mfma_f32_16x16x32_bf16 v[66:69], v[174:177], v[214:217], v[66:69]
	s_setprio 0
	s_barrier
	s_add_i32 s24, s47, s30
	v_lshl_add_u64 v[218:219], v[218:219], 0, s[78:79]
	s_mov_b32 m0, s24
	ds_read_b128 v[186:189], v227 offset:49152
	ds_read_b128 v[190:193], v227 offset:50176
	ds_read_b128 v[194:197], v227 offset:51200
	ds_read_b128 v[198:201], v227 offset:52224
	ds_read_b128 v[202:205], v227 offset:53248
	ds_read_b128 v[206:209], v227 offset:54272
	ds_read_b128 v[210:213], v227 offset:55296
	ds_read_b128 v[214:217], v227 offset:56320
	global_load_lds_dwordx4 v[218:219], off
	s_add_i32 m0, s24, 0x2000
	s_add_u32 s22, s22, 0x40080
	v_lshl_add_u64 v[218:219], v[238:239], 0, s[78:79]
	s_addc_u32 s23, s23, 0
	s_add_i32 s24, s49, s30
	global_load_lds_dwordx4 v[218:219], off
	v_lshl_add_u64 v[218:219], s[22:23], 0, v[0:1]
	s_mov_b32 m0, s24
	s_nop 0
	global_load_lds_dwordx4 v[218:219], off
	v_lshl_add_u64 v[218:219], s[22:23], 0, v[158:159]
	s_add_i32 m0, s24, 0x2000
	s_nop 0
	global_load_lds_dwordx4 v[218:219], off
	s_mov_b64 s[50:51], 0x4000
	v_lshl_add_u64 v[218:219], v[240:241], 0, s[50:51]
	s_mov_b32 m0, s37
	s_nop 0
	global_load_lds_dwordx4 v[218:219], off
	v_lshl_add_u64 v[218:219], v[242:243], 0, s[50:51]
	s_mov_b32 m0, s38
	s_nop 0
	global_load_lds_dwordx4 v[218:219], off
	s_waitcnt vmcnt(8)
	s_waitcnt lgkmcnt(0)
	s_barrier
	s_setprio 1
	s_waitcnt lgkmcnt(0)
	v_mfma_f32_16x16x32_bf16 v[62:65], v[130:133], v[186:189], v[62:65]
	v_mfma_f32_16x16x32_bf16 v[58:61], v[138:141], v[186:189], v[58:61]
	v_mfma_f32_16x16x32_bf16 v[46:49], v[130:133], v[194:197], v[46:49]
	v_mfma_f32_16x16x32_bf16 v[42:45], v[138:141], v[194:197], v[42:45]
	v_mfma_f32_16x16x32_bf16 v[30:33], v[130:133], v[202:205], v[30:33]
	v_mfma_f32_16x16x32_bf16 v[26:29], v[138:141], v[202:205], v[26:29]
	v_mfma_f32_16x16x32_bf16 v[14:17], v[130:133], v[210:213], v[14:17]
	v_mfma_f32_16x16x32_bf16 v[10:13], v[138:141], v[210:213], v[10:13]
	v_mfma_f32_16x16x32_bf16 v[62:65], v[134:137], v[190:193], v[62:65]
	v_mfma_f32_16x16x32_bf16 v[58:61], v[142:145], v[190:193], v[58:61]
	v_mfma_f32_16x16x32_bf16 v[46:49], v[134:137], v[198:201], v[46:49]
	v_mfma_f32_16x16x32_bf16 v[42:45], v[142:145], v[198:201], v[42:45]
	v_mfma_f32_16x16x32_bf16 v[30:33], v[134:137], v[206:209], v[30:33]
	v_mfma_f32_16x16x32_bf16 v[26:29], v[142:145], v[206:209], v[26:29]
	v_mfma_f32_16x16x32_bf16 v[14:17], v[134:137], v[214:217], v[14:17]
	v_mfma_f32_16x16x32_bf16 v[10:13], v[142:145], v[214:217], v[10:13]
	s_setprio 0
	s_setprio 1
	v_mfma_f32_16x16x32_bf16 v[54:57], v[146:149], v[186:189], v[54:57]
	v_mfma_f32_16x16x32_bf16 v[50:53], v[154:157], v[186:189], v[50:53]
	v_mfma_f32_16x16x32_bf16 v[38:41], v[146:149], v[194:197], v[38:41]
	v_mfma_f32_16x16x32_bf16 v[34:37], v[154:157], v[194:197], v[34:37]
	v_mfma_f32_16x16x32_bf16 v[22:25], v[146:149], v[202:205], v[22:25]
	v_mfma_f32_16x16x32_bf16 v[18:21], v[154:157], v[202:205], v[18:21]
	v_mfma_f32_16x16x32_bf16 v[6:9], v[146:149], v[210:213], v[6:9]
	v_mfma_f32_16x16x32_bf16 v[2:5], v[154:157], v[210:213], v[2:5]
	v_mfma_f32_16x16x32_bf16 v[54:57], v[150:153], v[190:193], v[54:57]
	v_mfma_f32_16x16x32_bf16 v[50:53], v[174:177], v[190:193], v[50:53]
	v_mfma_f32_16x16x32_bf16 v[38:41], v[150:153], v[198:201], v[38:41]
	v_mfma_f32_16x16x32_bf16 v[34:37], v[174:177], v[198:201], v[34:37]
	v_mfma_f32_16x16x32_bf16 v[22:25], v[150:153], v[206:209], v[22:25]
	v_mfma_f32_16x16x32_bf16 v[18:21], v[174:177], v[206:209], v[18:21]
	v_mfma_f32_16x16x32_bf16 v[6:9], v[150:153], v[214:217], v[6:9]
	v_mfma_f32_16x16x32_bf16 v[2:5], v[174:177], v[214:217], v[2:5]
	s_setprio 0
	s_barrier
	s_add_i32 s46, s46, 2
	s_add_u32 s10, s10, 0x8000
	s_addc_u32 s11, s11, 0
	s_add_u32 s44, s44, 0x100
	s_addc_u32 s45, s45, 0
	s_cmp_gt_u32 s46, 13
	s_cbranch_scc0 .LBB0_549
	s_and_b64 vcc, exec, s[4:5]
	s_cbranch_vccz .LBB0_552
	s_barrier
